# phase 1: each Fourier-fold item's two independent passes run on two different waves (all 2048 waves take one pass) instead of both passes on the first 1024 waves
# baseline (speedup 1.0000x reference)
.LBB0_90:
	s_or_b64 exec, exec, s[6:7]
	s_load_dwordx8 s[24:31], s[0:1], 0x68
	s_load_dwordx2 s[52:53], s[0:1], 0x88
	s_load_dwordx2 s[48:49], s[0:1], 0x98
	s_load_dwordx2 s[36:37], s[0:1], 0x0
	s_load_dwordx2 s[38:39], s[0:1], 0x10
	s_load_dwordx2 s[54:55], s[0:1], 0x40
	s_load_dwordx2 s[50:51], s[0:1], 0x30
	s_ashr_i32 s0, s8, 6
	s_lshl_b32 s96, s2, 3
	s_add_i32 s40, s0, s96
	s_mulk_i32 s0, 0x2100
	v_and_b32_e32 v2, 63, v1
	s_waitcnt lgkmcnt(0)
	s_lshl_b32 s42, s33, 3
	s_add_i32 s41, s0, 0
	s_mov_b32 s5, 0
	s_cmpk_gt_i32 s40, 0x3ff
	v_lshlrev_b32_e32 v68, 2, v2
	s_barrier
	v_lshlrev_b32_e32 v4, 3, v2
	v_and_b32_e32 v10, 24, v4
	v_mov_b32_e32 v5, 0
	v_lshlrev_b32_e32 v4, 1, v10
	s_bfe_u32 s0, s8, 0x20006
	v_lshl_add_u64 v[8:9], s[48:49], 0, v[4:5]
	s_mul_i32 s4, s0, 0x1f00000
	s_lshl_b32 s0, s0, 24
	s_mov_b32 s1, s5
	v_mov_b32_e32 v69, v5
	v_lshrrev_b32_e32 v22, 2, v2
	v_lshl_add_u64 v[8:9], v[8:9], 0, s[0:1]
	s_mov_b64 s[0:1], 0x400000
	v_lshl_add_u64 v[6:7], s[54:55], 0, v[68:69]
	v_add_u32_e32 v3, s41, v68
	v_lshl_add_u64 v[8:9], v[8:9], 0, s[0:1]
	s_movk_i32 s0, 0x104
	v_mov_b32_e32 v4, s41
	v_lshlrev_b32_e32 v25, 1, v22
	v_lshl_add_u64 v[6:7], v[6:7], 0, s[4:5]
	v_mad_u32_u24 v23, v10, s0, v4
	v_and_b32_e32 v24, 60, v2
	v_mul_u32_u24_e32 v26, 3, v22
	v_or_b32_e32 v27, 16, v22
	v_or_b32_e32 v28, 32, v25
	v_mad_u32_u24 v29, v22, 3, 48
	s_movk_i32 s10, 0xd00
	v_add_u32_e32 v30, 0x400, v3
	v_add_u32_e32 v31, 0x800, v3
	v_add_u32_e32 v32, 0xc00, v3
	v_add_u32_e32 v33, 0x1000, v3
	v_add_u32_e32 v34, 0x1400, v3
	v_add_u32_e32 v35, 0x1800, v3
	v_add_u32_e32 v36, 0x1c00, v3
	s_and_b32 s11, s40, 0x3ff
.LBB0_92:
	s_ashr_i32 s0, s11, 2
	s_lshl_b32 s4, s0, 6
	s_bfe_u32 s1, s0, 0x10007
	s_and_b32 s12, s4, 0x3c0
	s_lshl_b32 s4, s0, 1
	s_and_b32 s13, s4, 0xc0
	s_and_b32 s6, s4, 32
	s_lshl_b32 s4, s1, 8
	s_add_i32 s16, s4, 0
	s_add_i32 s16, s16, 0x10800
	s_cmp_eq_u32 s1, 0
	s_cselect_b32 s1, s10, 0xe00
	v_or_b32_e32 v37, s6, v22
	s_or_b32 s1, s1, s13
	v_or_b32_e32 v4, s1, v37
	s_bfe_u32 s0, s0, 0x10004
	v_lshlrev_b32_e32 v4, 11, v4
	v_lshl_or_b32 v38, s0, 7, v24
	s_lshl_b32 s1, s0, 6
	s_mulk_i32 s0, 0x60
	v_or_b32_e32 v41, s6, v27
	s_lshr_b32 s4, s40, 10
	s_lshl_b32 s4, s4, 5
	s_or_b32 s17, s13, 0x4b00
	s_or_b32 s18, s13, 0x6a00
	s_or_b32 s19, s13, 0x8900
	s_or_b32 s20, s13, 0xa800
	s_or_b32 s21, s13, 0xc700
	s_or_b32 s22, s13, 0xe600
	s_or_b32 s23, s13, 0x10500
	s_or_b32 s34, s13, 0x12400
	s_or_b32 s35, s13, 0x14300
	s_or_b32 s43, s13, 0x16200
	s_or_b32 s44, s13, 0x18100
	s_or_b32 s45, s13, 0x1a000
	s_or_b32 s46, s13, 0x1de00
	s_or_b32 s47, s13, 0x21c00
	s_or_b32 s56, s13, 0x23b00
	s_or_b32 s57, s13, 0x25a00
	s_or_b32 s58, s13, 0x27900
	s_or_b32 s59, s13, 0x29800
	s_or_b32 s60, s13, 0x2b700
	s_or_b32 s61, s13, 0x2d600
	s_or_b32 s62, s13, 0x2f500
	s_or_b32 s63, s13, 0x31400
	s_or_b32 s64, s13, 0x33300
	s_or_b32 s65, s13, 0x35200
	s_or_b32 s66, s13, 0x37100
	s_or_b32 s67, s13, 0x39000
	s_or_b32 s68, s13, 0x3ce00
	v_or_b32_e32 v10, 0x8000, v4
	v_mov_b32_e32 v11, v5
	s_or_b32 s69, s13, 0x2c00
	s_or_b32 s70, s13, 0x1bf00
	s_or_b32 s71, s13, 0x1fd00
	s_or_b32 s72, s13, 0x3af00
	v_or_b32_e32 v39, s1, v25
	v_add_u32_e32 v40, s0, v26
	v_lshlrev_b32_e32 v42, 2, v41
	v_or_b32_e32 v43, s1, v28
	v_add_u32_e32 v44, s0, v29
	s_mov_b64 s[8:9], 0
